# phase 1 epilogue: rope cos/sin rows of the 4 sub-blocks of each half loaded together at the start of the half into v206-v237 (one wait per half instead of one per sub-block)
# speedup vs baseline: 1.0011x; 1.0011x over previous
; template <int AI>
; __device__ __forceinline__ void epi_inproj(const Params& p, const acc8_t& acc, int g, int tbase, int fr, int fq) {
;     ...
;   if (gain) {
; #pragma unroll
;     for (int bj = 0; bj < 2; bj++)
; #pragma unroll
;       for (int n = 0; n < 2; n++) gg[bj][n] = *(const float4*)(gain + 32 * bj + 16 * n + 4 * fq);
;   }
; #pragma unroll
;   for (int m = 0; m < 4; m++) {
;     const int tl = 16 * m + fr;
;     float x[16];
; #pragma unroll
;     for (int bj = 0; bj < 2; bj++)
; #pragma unroll
;       for (int n = 0; n < 2; n++)
; #pragma unroll
;         for (int j = 0; j < 4; j++) x[(bj * 2 + n) * 4 + j] = acc[AI][bj][m][n][j];
;     if (wi) {
;       if (fq < 2) *(float4*)((float*)(ws + OFF_WI) + (size_t)(tbase + tl) * 8 + 4 * fq) = make_float4(x[0], x[1], x[2], x[3]);
;       continue;
;     }
;     if (gain) {
;       float ss = 0.f;
; #pragma unroll
;       for (int k = 0; k < 16; k++) ss += x[k] * x[k];
;       ss = xsum16(ss);
;       ss = xsum32(ss);
;       const float rs = rsqrtf(ss * (1.f / 64.f) + 1e-6f);
; #pragma unroll
;       for (int bj = 0; bj < 2; bj++)
; #pragma unroll
;         for (int n = 0; n < 2; n++) {
;           x[(bj * 2 + n) * 4 + 0] *= rs * gg[bj][n].x; x[(bj * 2 + n) * 4 + 1] *= rs * gg[bj][n].y;
;           x[(bj * 2 + n) * 4 + 2] *= rs * gg[bj][n].z; x[(bj * 2 + n) * 4 + 3] *= rs * gg[bj][n].w;
;         }
;     }
;     if (rope) {
;       const int pos = sample ? 1024 + tl : trow + tl;
;       const float4* cs = (const float4*)((const float2*)(ws + OFF_CS) + (size_t)pos * 8 + 4 * (fq & 1));
;       const float4 c01 = cs[0], c23 = cs[1];
;       const float cc[4] = {c01.x, c01.z, c23.x, c23.z};
;       const float sn[4] = {c01.y, c01.w, c23.y, c23.w};
; #pragma unroll
;       for (int j = 0; j < 4; j++) {
;         const float other = xother32(x[j], fq < 2);
;         x[j] = (fq < 2) ? x[j] * cc[j] - other * sn[j] : x[j] * cc[j] + other * sn[j];
;       }
;     }
.LBB0_282:
	s_xor_b64 s[22:23], s[22:23], -1
	s_and_b64 s[4:5], s[4:5], exec
	s_cselect_b32 s1, 0x400, s64
	s_cmp_lg_u64 s[12:13], 0
	s_cselect_b64 s[96:97], -1, 0
	s_ashr_i32 s93, s92, 31
	s_lshl_b64 s[6:7], s[92:93], 1
	s_add_u32 s6, s12, s6
	s_addc_u32 s7, s13, s7
	s_cmp_lg_u64 s[18:19], 0
	v_and_b32_e32 v148, 4, v146
	s_cselect_b64 s[94:95], -1, 0
	s_lshr_b32 s64, s43, 6
	v_lshlrev_b32_e32 v154, 3, v148
	v_and_b32_e32 v148, 1, v160
	s_lshl_b64 s[12:13], s[64:65], 13
	v_cmp_eq_u32_e64 s[8:9], 0, v148
	v_and_b32_e32 v148, 2, v160
	s_add_u32 s12, s18, s12
	v_lshl_add_u64 v[166:167], v[146:147], 1, s[6:7]
	v_cmp_eq_u32_e64 s[6:7], 0, v148
	s_addc_u32 s13, s19, s13
	v_and_b32_e32 v148, -4, v160
	v_ashrrev_i32_e32 v149, 31, v148
	s_cmp_lg_u64 s[28:29], 0
	s_mov_b32 s43, s65
	v_lshl_add_u64 v[164:165], v[148:149], 1, s[12:13]
	s_cselect_b64 s[92:93], -1, 0
	s_lshl_b64 s[12:13], s[42:43], 2
	s_add_u32 s12, s28, s12
	s_addc_u32 s13, s29, s13
	v_lshlrev_b64 v[170:171], 2, v[146:147]
	v_cndmask_b32_e64 v146, 0, 1, s[10:11]
	v_lshl_add_u64 v[168:169], s[52:53], 0, v[154:155]
	v_cmp_gt_i32_e64 s[4:5], 2, v192
	v_lshl_add_u64 v[162:163], s[12:13], 0, v[170:171]
	s_mov_b64 s[12:13], -1
	s_and_b64 vcc, s[84:85], s[22:23]
	s_andn2_b64 vcc, exec, vcc
	s_cbranch_vccnz .Lp1cs_a_skip
	v_add_u32_e32 v210, s1, v160
	v_ashrrev_i32_e32 v211, 31, v210
	v_lshlrev_b64 v[210:211], 6, v[210:211]
	v_lshl_add_u64 v[210:211], v[168:169], 0, v[210:211]
	global_load_dwordx4 v[206:209], v[210:211], off offset:16
	s_nop 0
	global_load_dwordx4 v[210:213], v[210:211], off
	v_add3_u32 v218, s1, v160, 16
	v_ashrrev_i32_e32 v219, 31, v218
	v_lshlrev_b64 v[218:219], 6, v[218:219]
	v_lshl_add_u64 v[218:219], v[168:169], 0, v[218:219]
	global_load_dwordx4 v[214:217], v[218:219], off offset:16
	s_nop 0
	global_load_dwordx4 v[218:221], v[218:219], off
	v_add3_u32 v226, s1, v160, 32
	v_ashrrev_i32_e32 v227, 31, v226
	v_lshlrev_b64 v[226:227], 6, v[226:227]
	v_lshl_add_u64 v[226:227], v[168:169], 0, v[226:227]
	global_load_dwordx4 v[222:225], v[226:227], off offset:16
	s_nop 0
	global_load_dwordx4 v[226:229], v[226:227], off
	v_add3_u32 v234, s1, v160, 48
	v_ashrrev_i32_e32 v235, 31, v234
	v_lshlrev_b64 v[234:235], 6, v[234:235]
	v_lshl_add_u64 v[234:235], v[168:169], 0, v[234:235]
	global_load_dwordx4 v[230:233], v[234:235], off offset:16
	s_nop 0
	global_load_dwordx4 v[234:237], v[234:235], off
.Lp1cs_a_skip:
	s_and_b64 vcc, exec, s[22:23]
	v_cmp_ne_u32_e64 s[10:11], 1, v146
	s_cbranch_vccz .LBB0_294
	s_and_b64 vcc, exec, s[10:11]
	s_cbranch_vccnz .LBB0_365
	v_mul_f32_e32 v146, v123, v123
	v_fmac_f32_e32 v146, v122, v122
	v_fmac_f32_e32 v146, v124, v124
	v_fmac_f32_e32 v146, v125, v125
	v_fmac_f32_e32 v146, v126, v126
	v_fmac_f32_e32 v146, v127, v127
	v_fmac_f32_e32 v146, v128, v128
	v_fmac_f32_e32 v146, v129, v129
	v_fmac_f32_e32 v146, v118, v118
	v_fmac_f32_e32 v146, v119, v119
	v_fmac_f32_e32 v146, v120, v120
	v_fmac_f32_e32 v146, v121, v121
	v_fmac_f32_e32 v146, v114, v114
	v_fmac_f32_e32 v146, v115, v115
	v_fmac_f32_e32 v146, v116, v116
	v_fmac_f32_e32 v146, v117, v117
	v_mov_b32_e32 v147, v146
	s_nop 1
	v_permlane16_swap_b32_e32 v146, v147
	v_add_f32_e32 v146, v146, v147
	v_mov_b32_e32 v147, v146
	s_nop 1
	v_permlane32_swap_b32_e32 v146, v147
	v_add_f32_e32 v146, v146, v147
	v_fmamk_f32 v146, v146, 0x3c800000, v191
	v_mul_f32_e32 v147, 0x4b800000, v146
	v_cmp_gt_f32_e32 vcc, s59, v146
	s_nop 1
	v_cndmask_b32_e32 v146, v146, v147, vcc
	v_rsq_f32_e32 v146, v146
	s_nop 0
	v_mul_f32_e32 v147, 0x45800000, v146
	v_cndmask_b32_e32 v146, v146, v147, vcc
	s_waitcnt vmcnt(0)
	v_pk_mul_f32 v[194:195], v[130:131], v[146:147] op_sel_hi:[1,0]
	v_pk_mul_f32 v[148:149], v[132:133], v[146:147] op_sel_hi:[1,0]
	v_pk_mul_f32 v[196:197], v[134:135], v[146:147] op_sel_hi:[1,0]
	v_pk_mul_f32 v[198:199], v[136:137], v[146:147] op_sel_hi:[1,0]
	v_pk_mul_f32 v[200:201], v[138:139], v[146:147] op_sel_hi:[1,0]
	v_pk_mul_f32 v[202:203], v[140:141], v[146:147] op_sel_hi:[1,0]
	v_pk_mul_f32 v[204:205], v[142:143], v[146:147] op_sel_hi:[1,0]
	v_pk_mul_f32 v[146:147], v[144:145], v[146:147] op_sel_hi:[1,0]
	v_pk_mul_f32 v[114:115], v[114:115], v[204:205]
	v_pk_mul_f32 v[116:117], v[116:117], v[146:147]
	v_pk_mul_f32 v[120:121], v[120:121], v[202:203]
	v_pk_mul_f32 v[118:119], v[118:119], v[200:201]
	v_pk_mul_f32 v[128:129], v[128:129], v[198:199]
	v_pk_mul_f32 v[126:127], v[126:127], v[196:197]
	v_pk_mul_f32 v[148:149], v[124:125], v[148:149]
	v_pk_mul_f32 v[146:147], v[122:123], v[194:195]
	s_andn2_b64 vcc, exec, s[84:85]
	s_cbranch_vccnz .LBB0_286
.LBB0_285:
	v_mov_b32_e32 v154, v146
	v_mov_b32_e32 v161, v146
	v_mov_b32_e32 v193, v147
	v_mov_b32_e32 v202, v147
	v_permlane32_swap_b32_e32 v154, v161
	s_nop 0
	v_permlane32_swap_b32_e32 v193, v202
	v_cndmask_b32_e64 v203, v193, v202, s[4:5]
	v_cndmask_b32_e64 v202, v154, v161, s[4:5]
	v_mov_b32_e32 v154, v148
	v_mov_b32_e32 v161, v148
	v_mov_b32_e32 v193, v149
	s_nop 0
	v_permlane32_swap_b32_e32 v154, v161
	s_waitcnt vmcnt(0)
	v_mov_b64_e32 v[194:195], v[206:207]
	v_mov_b64_e32 v[196:197], v[208:209]
	v_mov_b64_e32 v[198:199], v[210:211]
	v_mov_b64_e32 v[200:201], v[212:213]
	v_mov_b32_e32 v205, v200
	v_mov_b32_e32 v200, v199
	v_mov_b32_e32 v204, v198
	v_pk_mul_f32 v[198:199], v[200:201], v[202:203]
	v_mov_b32_e32 v201, v196
	v_cndmask_b32_e64 v199, v199, -v199, s[4:5]
	v_cndmask_b32_e64 v198, v198, -v198, s[4:5]
	v_pk_fma_f32 v[146:147], v[146:147], v[204:205], v[198:199]
	v_mov_b32_e32 v198, v149
	s_nop 1
	v_permlane32_swap_b32_e32 v193, v198
	v_cndmask_b32_e64 v199, v193, v198, s[4:5]
	v_cndmask_b32_e64 v198, v154, v161, s[4:5]
	v_mov_b32_e32 v196, v195
	v_mov_b32_e32 v200, v194
	v_pk_mul_f32 v[194:195], v[196:197], v[198:199]
	s_nop 0
	v_cndmask_b32_e64 v195, v195, -v195, s[4:5]
	v_cndmask_b32_e64 v194, v194, -v194, s[4:5]
	v_pk_fma_f32 v[148:149], v[148:149], v[200:201], v[194:195]

; template <int AI>
; __device__ __forceinline__ void epi_inproj(const Params& p, const acc8_t& acc, int g, int tbase, int fr, int fq) {
;     ...
;     if (rope) {
;       const int pos = sample ? 1024 + tl : trow + tl;
;       const float4* cs = (const float4*)((const float2*)(ws + OFF_CS) + (size_t)pos * 8 + 4 * (fq & 1));
;       const float4 c01 = cs[0], c23 = cs[1];
;       const float cc[4] = {c01.x, c01.z, c23.x, c23.z};
;       const float sn[4] = {c01.y, c01.w, c23.y, c23.w};
; #pragma unroll
;       for (int j = 0; j < 4; j++) {
;         const float other = xother32(x[j], fq < 2);
;         x[j] = (fq < 2) ? x[j] * cc[j] - other * sn[j] : x[j] * cc[j] + other * sn[j];
;       }
;     }
.LBB0_306:
	v_mov_b32_e32 v121, v114
	v_mov_b32_e32 v146, v114
	v_mov_b32_e32 v147, v115
	v_mov_b32_e32 v148, v115
	v_permlane32_swap_b32_e32 v121, v146
	s_nop 0
	v_permlane32_swap_b32_e32 v147, v148
	v_cndmask_b32_e64 v147, v147, v148, s[4:5]
	v_cndmask_b32_e64 v146, v121, v146, s[4:5]
	v_mov_b32_e32 v121, v116
	v_mov_b64_e32 v[122:123], v[214:215]
	v_mov_b64_e32 v[124:125], v[216:217]
	v_mov_b64_e32 v[126:127], v[218:219]
	v_mov_b64_e32 v[128:129], v[220:221]
	v_mov_b32_e32 v149, v128
	v_mov_b32_e32 v128, v127
	v_mov_b32_e32 v148, v126
	v_pk_mul_f32 v[126:127], v[128:129], v[146:147]
	v_mov_b32_e32 v128, v117
	v_cndmask_b32_e64 v127, v127, -v127, s[4:5]
	v_cndmask_b32_e64 v126, v126, -v126, s[4:5]
	v_pk_fma_f32 v[114:115], v[114:115], v[148:149], v[126:127]
	v_mov_b32_e32 v126, v116
	v_mov_b32_e32 v127, v117
	s_nop 0
	v_permlane32_swap_b32_e32 v121, v126
	v_permlane32_swap_b32_e32 v127, v128
	v_cndmask_b32_e64 v127, v127, v128, s[4:5]
	v_cndmask_b32_e64 v126, v121, v126, s[4:5]
	v_mov_b32_e32 v129, v124
	v_mov_b32_e32 v124, v123
	v_mov_b32_e32 v128, v122
	v_pk_mul_f32 v[122:123], v[124:125], v[126:127]
	s_nop 0
	v_cndmask_b32_e64 v123, v123, -v123, s[4:5]
	v_cndmask_b32_e64 v122, v122, -v122, s[4:5]
	v_pk_fma_f32 v[116:117], v[116:117], v[128:129], v[122:123]

; template <int AI>
; __device__ __forceinline__ void epi_inproj(const Params& p, const acc8_t& acc, int g, int tbase, int fr, int fq) {
;     ...
;     if (rope) {
;       const int pos = sample ? 1024 + tl : trow + tl;
;       const float4* cs = (const float4*)((const float2*)(ws + OFF_CS) + (size_t)pos * 8 + 4 * (fq & 1));
;       const float4 c01 = cs[0], c23 = cs[1];
;       const float cc[4] = {c01.x, c01.z, c23.x, c23.z};
;       const float sn[4] = {c01.y, c01.w, c23.y, c23.w};
; #pragma unroll
;       for (int j = 0; j < 4; j++) {
;         const float other = xother32(x[j], fq < 2);
;         x[j] = (fq < 2) ? x[j] * cc[j] - other * sn[j] : x[j] * cc[j] + other * sn[j];
;       }
;     }
.LBB0_320:
	v_mov_b32_e32 v103, v98
	v_mov_b32_e32 v112, v98
	v_mov_b32_e32 v113, v99
	v_mov_b32_e32 v114, v99
	v_permlane32_swap_b32_e32 v103, v112
	s_nop 0
	v_permlane32_swap_b32_e32 v113, v114
	v_cndmask_b32_e64 v113, v113, v114, s[4:5]
	v_cndmask_b32_e64 v112, v103, v112, s[4:5]
	v_mov_b32_e32 v103, v100
	v_mov_b64_e32 v[104:105], v[222:223]
	v_mov_b64_e32 v[106:107], v[224:225]
	v_mov_b64_e32 v[108:109], v[226:227]
	v_mov_b64_e32 v[110:111], v[228:229]
	v_mov_b32_e32 v115, v110
	v_mov_b32_e32 v110, v109
	v_mov_b32_e32 v114, v108
	v_pk_mul_f32 v[108:109], v[110:111], v[112:113]
	v_mov_b32_e32 v110, v101
	v_cndmask_b32_e64 v109, v109, -v109, s[4:5]
	v_cndmask_b32_e64 v108, v108, -v108, s[4:5]
	v_pk_fma_f32 v[98:99], v[98:99], v[114:115], v[108:109]
	v_mov_b32_e32 v108, v100
	v_mov_b32_e32 v109, v101
	s_nop 0
	v_permlane32_swap_b32_e32 v103, v108
	v_permlane32_swap_b32_e32 v109, v110
	v_cndmask_b32_e64 v109, v109, v110, s[4:5]
	v_cndmask_b32_e64 v108, v103, v108, s[4:5]
	v_mov_b32_e32 v111, v106
	v_mov_b32_e32 v106, v105
	v_mov_b32_e32 v110, v104
	v_pk_mul_f32 v[104:105], v[106:107], v[108:109]
	s_nop 0
	v_cndmask_b32_e64 v105, v105, -v105, s[4:5]
	v_cndmask_b32_e64 v104, v104, -v104, s[4:5]
	v_pk_fma_f32 v[100:101], v[100:101], v[110:111], v[104:105]

; template <int AI>
; __device__ __forceinline__ void epi_inproj(const Params& p, const acc8_t& acc, int g, int tbase, int fr, int fq) {
;     ...
;     if (rope) {
;       const int pos = sample ? 1024 + tl : trow + tl;
;       const float4* cs = (const float4*)((const float2*)(ws + OFF_CS) + (size_t)pos * 8 + 4 * (fq & 1));
;       const float4 c01 = cs[0], c23 = cs[1];
;       const float cc[4] = {c01.x, c01.z, c23.x, c23.z};
;       const float sn[4] = {c01.y, c01.w, c23.y, c23.w};
; #pragma unroll
;       for (int j = 0; j < 4; j++) {
;         const float other = xother32(x[j], fq < 2);
;         x[j] = (fq < 2) ? x[j] * cc[j] - other * sn[j] : x[j] * cc[j] + other * sn[j];
;       }
;     }
.LBB0_334:
	v_mov_b32_e32 v87, v82
	v_mov_b32_e32 v96, v82
	v_mov_b32_e32 v97, v83
	v_mov_b32_e32 v98, v83
	v_permlane32_swap_b32_e32 v87, v96
	s_nop 0
	v_permlane32_swap_b32_e32 v97, v98
	v_cndmask_b32_e64 v97, v97, v98, s[4:5]
	v_cndmask_b32_e64 v96, v87, v96, s[4:5]
	v_mov_b32_e32 v87, v84
	v_mov_b64_e32 v[88:89], v[230:231]
	v_mov_b64_e32 v[90:91], v[232:233]
	v_mov_b64_e32 v[92:93], v[234:235]
	v_mov_b64_e32 v[94:95], v[236:237]
	v_mov_b32_e32 v99, v94
	v_mov_b32_e32 v94, v93
	v_mov_b32_e32 v98, v92
	v_pk_mul_f32 v[92:93], v[94:95], v[96:97]
	v_mov_b32_e32 v94, v85
	v_cndmask_b32_e64 v93, v93, -v93, s[4:5]
	v_cndmask_b32_e64 v92, v92, -v92, s[4:5]
	v_pk_fma_f32 v[82:83], v[82:83], v[98:99], v[92:93]
	v_mov_b32_e32 v92, v84
	v_mov_b32_e32 v93, v85
	s_nop 0
	v_permlane32_swap_b32_e32 v87, v92
	v_permlane32_swap_b32_e32 v93, v94
	v_cndmask_b32_e64 v93, v93, v94, s[4:5]
	v_cndmask_b32_e64 v92, v87, v92, s[4:5]
	v_mov_b32_e32 v95, v90
	v_mov_b32_e32 v90, v89
	v_mov_b32_e32 v94, v88
	v_pk_mul_f32 v[88:89], v[90:91], v[92:93]
	s_nop 0
	v_cndmask_b32_e64 v89, v89, -v89, s[4:5]
	v_cndmask_b32_e64 v88, v88, -v88, s[4:5]
	v_pk_fma_f32 v[84:85], v[84:85], v[94:95], v[88:89]

; template <int AI>
; __device__ __forceinline__ void epi_inproj(const Params& p, const acc8_t& acc, int g, int tbase, int fr, int fq) {
;     ...
;   if (gain) {
; #pragma unroll
;     for (int bj = 0; bj < 2; bj++)
; #pragma unroll
;       for (int n = 0; n < 2; n++) gg[bj][n] = *(const float4*)(gain + 32 * bj + 16 * n + 4 * fq);
;   }
; #pragma unroll
;   for (int m = 0; m < 4; m++) {
;     const int tl = 16 * m + fr;
;     float x[16];
; #pragma unroll
;     for (int bj = 0; bj < 2; bj++)
; #pragma unroll
;       for (int n = 0; n < 2; n++)
; #pragma unroll
;         for (int j = 0; j < 4; j++) x[(bj * 2 + n) * 4 + j] = acc[AI][bj][m][n][j];
;     if (wi) {
;       if (fq < 2) *(float4*)((float*)(ws + OFF_WI) + (size_t)(tbase + tl) * 8 + 4 * fq) = make_float4(x[0], x[1], x[2], x[3]);
;       continue;
;     }
;     if (gain) {
;       float ss = 0.f;
; #pragma unroll
;       for (int k = 0; k < 16; k++) ss += x[k] * x[k];
;       ss = xsum16(ss);
;       ss = xsum32(ss);
;       const float rs = rsqrtf(ss * (1.f / 64.f) + 1e-6f);
; #pragma unroll
;       for (int bj = 0; bj < 2; bj++)
; #pragma unroll
;         for (int n = 0; n < 2; n++) {
;           x[(bj * 2 + n) * 4 + 0] *= rs * gg[bj][n].x; x[(bj * 2 + n) * 4 + 1] *= rs * gg[bj][n].y;
;           x[(bj * 2 + n) * 4 + 2] *= rs * gg[bj][n].z; x[(bj * 2 + n) * 4 + 3] *= rs * gg[bj][n].w;
;         }
;     }
;     if (rope) {
;       const int pos = sample ? 1024 + tl : trow + tl;
;       const float4* cs = (const float4*)((const float2*)(ws + OFF_CS) + (size_t)pos * 8 + 4 * (fq & 1));
;       const float4 c01 = cs[0], c23 = cs[1];
;       const float cc[4] = {c01.x, c01.z, c23.x, c23.z};
;       const float sn[4] = {c01.y, c01.w, c23.y, c23.w};
; #pragma unroll
;       for (int j = 0; j < 4; j++) {
;         const float other = xother32(x[j], fq < 2);
;         x[j] = (fq < 2) ? x[j] * cc[j] - other * sn[j] : x[j] * cc[j] + other * sn[j];
;       }
;     }
.LBB0_394:
	s_xor_b64 s[22:23], s[22:23], -1
	s_and_b64 s[4:5], s[4:5], exec
	s_cselect_b32 s0, 0x400, s64
	s_cmp_lg_u64 s[12:13], 0
	s_cselect_b64 s[94:95], -1, 0
	s_ashr_i32 s85, s84, 31
	s_lshl_b64 s[6:7], s[84:85], 1
	s_add_u32 s6, s12, s6
	s_addc_u32 s7, s13, s7
	s_cmp_lg_u64 s[18:19], 0
	v_and_b32_e32 v84, 4, v82
	s_cselect_b64 s[92:93], -1, 0
	s_lshr_b32 s64, s1, 6
	v_lshlrev_b32_e32 v154, 3, v84
	v_and_b32_e32 v84, 1, v160
	s_lshl_b64 s[12:13], s[64:65], 13
	v_cmp_eq_u32_e64 s[8:9], 0, v84
	v_and_b32_e32 v84, 2, v160
	s_add_u32 s12, s18, s12
	v_lshl_add_u64 v[90:91], v[82:83], 1, s[6:7]
	v_cmp_eq_u32_e64 s[6:7], 0, v84
	s_addc_u32 s13, s19, s13
	v_and_b32_e32 v84, -4, v160
	v_ashrrev_i32_e32 v85, 31, v84
	s_cmp_lg_u64 s[28:29], 0
	s_mov_b32 s43, s65
	v_lshl_add_u64 v[88:89], v[84:85], 1, s[12:13]
	s_cselect_b64 s[84:85], -1, 0
	s_lshl_b64 s[12:13], s[42:43], 2
	s_add_u32 s12, s28, s12
	s_addc_u32 s13, s29, s13
	v_lshlrev_b64 v[94:95], 2, v[82:83]
	v_cndmask_b32_e64 v82, 0, 1, s[10:11]
	v_readlane_b32 s28, v238, 26
	v_lshl_add_u64 v[92:93], s[52:53], 0, v[154:155]
	v_cmp_gt_i32_e64 s[4:5], 2, v192
	v_lshl_add_u64 v[86:87], s[12:13], 0, v[94:95]
	s_mov_b64 s[12:13], -1
	s_and_b64 vcc, s[82:83], s[22:23]
	s_andn2_b64 vcc, exec, vcc
	s_cbranch_vccnz .Lp1cs_b_skip
	v_add_u32_e32 v210, s0, v160
	v_ashrrev_i32_e32 v211, 31, v210
	v_lshlrev_b64 v[210:211], 6, v[210:211]
	v_lshl_add_u64 v[210:211], v[92:93], 0, v[210:211]
	global_load_dwordx4 v[206:209], v[210:211], off offset:16
	s_nop 0
	global_load_dwordx4 v[210:213], v[210:211], off
	v_add3_u32 v218, s0, v160, 16
	v_ashrrev_i32_e32 v219, 31, v218
	v_lshlrev_b64 v[218:219], 6, v[218:219]
	v_lshl_add_u64 v[218:219], v[92:93], 0, v[218:219]
	global_load_dwordx4 v[214:217], v[218:219], off offset:16
	s_nop 0
	global_load_dwordx4 v[218:221], v[218:219], off
	v_add3_u32 v226, s0, v160, 32
	v_ashrrev_i32_e32 v227, 31, v226
	v_lshlrev_b64 v[226:227], 6, v[226:227]
	v_lshl_add_u64 v[226:227], v[92:93], 0, v[226:227]
	global_load_dwordx4 v[222:225], v[226:227], off offset:16
	s_nop 0
	global_load_dwordx4 v[226:229], v[226:227], off
	v_add3_u32 v234, s0, v160, 48
	v_ashrrev_i32_e32 v235, 31, v234
	v_lshlrev_b64 v[234:235], 6, v[234:235]
	v_lshl_add_u64 v[234:235], v[92:93], 0, v[234:235]
	global_load_dwordx4 v[230:233], v[234:235], off offset:16
	s_nop 0
	global_load_dwordx4 v[234:237], v[234:235], off
.Lp1cs_b_skip:
	s_and_b64 vcc, exec, s[22:23]
	v_cmp_ne_u32_e64 s[10:11], 1, v82
	v_readlane_b32 s29, v238, 27
	s_cbranch_vccz .LBB0_406
	s_and_b64 vcc, exec, s[10:11]
	s_cbranch_vccnz .LBB0_461
	v_mul_f32_e32 v82, v59, v59
	v_fmac_f32_e32 v82, v58, v58
	v_fmac_f32_e32 v82, v60, v60
	v_fmac_f32_e32 v82, v61, v61
	v_fmac_f32_e32 v82, v62, v62
	v_fmac_f32_e32 v82, v63, v63
	v_fmac_f32_e32 v82, v64, v64
	v_fmac_f32_e32 v82, v65, v65
	v_fmac_f32_e32 v82, v54, v54
	v_fmac_f32_e32 v82, v55, v55
	v_fmac_f32_e32 v82, v56, v56
	v_fmac_f32_e32 v82, v57, v57
	v_fmac_f32_e32 v82, v50, v50
	v_fmac_f32_e32 v82, v51, v51
	v_fmac_f32_e32 v82, v52, v52
	v_fmac_f32_e32 v82, v53, v53
	v_mov_b32_e32 v83, v82
	s_nop 1
	v_permlane16_swap_b32_e32 v82, v83
	v_add_f32_e32 v82, v82, v83
	v_mov_b32_e32 v83, v82
	s_nop 1
	v_permlane32_swap_b32_e32 v82, v83
	v_add_f32_e32 v82, v82, v83
	v_fmamk_f32 v82, v82, 0x3c800000, v191
	v_mul_f32_e32 v83, 0x4b800000, v82
	v_cmp_gt_f32_e32 vcc, s59, v82
	s_nop 1
	v_cndmask_b32_e32 v82, v82, v83, vcc
	v_rsq_f32_e32 v82, v82
	s_nop 0
	v_mul_f32_e32 v83, 0x45800000, v82
	v_cndmask_b32_e32 v82, v82, v83, vcc
	s_waitcnt vmcnt(0)
	v_pk_mul_f32 v[96:97], v[66:67], v[82:83] op_sel_hi:[1,0]
	v_pk_mul_f32 v[84:85], v[68:69], v[82:83] op_sel_hi:[1,0]
	v_pk_mul_f32 v[98:99], v[70:71], v[82:83] op_sel_hi:[1,0]
	v_pk_mul_f32 v[100:101], v[72:73], v[82:83] op_sel_hi:[1,0]
	v_pk_mul_f32 v[102:103], v[74:75], v[82:83] op_sel_hi:[1,0]
	v_pk_mul_f32 v[104:105], v[76:77], v[82:83] op_sel_hi:[1,0]
	v_pk_mul_f32 v[106:107], v[78:79], v[82:83] op_sel_hi:[1,0]
	v_pk_mul_f32 v[82:83], v[80:81], v[82:83] op_sel_hi:[1,0]
	v_pk_mul_f32 v[50:51], v[50:51], v[106:107]
	v_pk_mul_f32 v[52:53], v[52:53], v[82:83]
	v_pk_mul_f32 v[56:57], v[56:57], v[104:105]
	v_pk_mul_f32 v[54:55], v[54:55], v[102:103]
	v_pk_mul_f32 v[64:65], v[64:65], v[100:101]
	v_pk_mul_f32 v[62:63], v[62:63], v[98:99]
	v_pk_mul_f32 v[84:85], v[60:61], v[84:85]
	v_pk_mul_f32 v[82:83], v[58:59], v[96:97]
	s_andn2_b64 vcc, exec, s[82:83]
	s_cbranch_vccnz .LBB0_398
.LBB0_397:
	v_mov_b32_e32 v104, v82
	v_mov_b32_e32 v106, v82
	v_mov_b32_e32 v105, v83
	v_mov_b32_e32 v107, v83
	v_permlane32_swap_b32_e32 v104, v106
	s_nop 0
	v_permlane32_swap_b32_e32 v105, v107
	v_cndmask_b32_e64 v105, v105, v107, s[4:5]
	v_cndmask_b32_e64 v104, v104, v106, s[4:5]
	s_waitcnt vmcnt(0)
	v_mov_b64_e32 v[96:97], v[206:207]
	v_mov_b64_e32 v[98:99], v[208:209]
	v_mov_b64_e32 v[100:101], v[210:211]
	v_mov_b64_e32 v[102:103], v[212:213]
	v_mov_b32_e32 v107, v102
	v_mov_b32_e32 v102, v101
	v_mov_b32_e32 v106, v100
	v_pk_mul_f32 v[100:101], v[102:103], v[104:105]
	v_mov_b32_e32 v102, v84
	v_cndmask_b32_e64 v101, v101, -v101, s[4:5]
	v_cndmask_b32_e64 v100, v100, -v100, s[4:5]
	v_pk_fma_f32 v[82:83], v[82:83], v[106:107], v[100:101]
	v_mov_b32_e32 v100, v84
	v_mov_b32_e32 v101, v85
	v_mov_b32_e32 v103, v85
	v_permlane32_swap_b32_e32 v100, v102
	s_nop 0
	v_permlane32_swap_b32_e32 v101, v103
	v_cndmask_b32_e64 v101, v101, v103, s[4:5]
	v_cndmask_b32_e64 v100, v100, v102, s[4:5]
	v_mov_b32_e32 v103, v98
	v_mov_b32_e32 v98, v97
	v_mov_b32_e32 v102, v96
	v_pk_mul_f32 v[96:97], v[98:99], v[100:101]
	s_nop 0
	v_cndmask_b32_e64 v97, v97, -v97, s[4:5]
	v_cndmask_b32_e64 v96, v96, -v96, s[4:5]
	v_pk_fma_f32 v[84:85], v[84:85], v[102:103], v[96:97]

; template <int AI>
; __device__ __forceinline__ void epi_inproj(const Params& p, const acc8_t& acc, int g, int tbase, int fr, int fq) {
;     ...
;     if (rope) {
;       const int pos = sample ? 1024 + tl : trow + tl;
;       const float4* cs = (const float4*)((const float2*)(ws + OFF_CS) + (size_t)pos * 8 + 4 * (fq & 1));
;       const float4 c01 = cs[0], c23 = cs[1];
;       const float cc[4] = {c01.x, c01.z, c23.x, c23.z};
;       const float sn[4] = {c01.y, c01.w, c23.y, c23.w};
; #pragma unroll
;       for (int j = 0; j < 4; j++) {
;         const float other = xother32(x[j], fq < 2);
;         x[j] = (fq < 2) ? x[j] * cc[j] - other * sn[j] : x[j] * cc[j] + other * sn[j];
;       }
;     }
.LBB0_417:
	v_mov_b32_e32 v57, v50
	v_mov_b32_e32 v82, v50
	v_mov_b32_e32 v83, v51
	v_mov_b32_e32 v84, v51
	v_permlane32_swap_b32_e32 v57, v82
	s_nop 0
	v_permlane32_swap_b32_e32 v83, v84
	v_cndmask_b32_e64 v83, v83, v84, s[4:5]
	v_cndmask_b32_e64 v82, v57, v82, s[4:5]
	v_mov_b32_e32 v57, v52
	v_mov_b64_e32 v[58:59], v[214:215]
	v_mov_b64_e32 v[60:61], v[216:217]
	v_mov_b64_e32 v[62:63], v[218:219]
	v_mov_b64_e32 v[64:65], v[220:221]
	v_mov_b32_e32 v85, v64
	v_mov_b32_e32 v64, v63
	v_mov_b32_e32 v84, v62
	v_pk_mul_f32 v[62:63], v[64:65], v[82:83]
	v_mov_b32_e32 v64, v53
	v_cndmask_b32_e64 v63, v63, -v63, s[4:5]
	v_cndmask_b32_e64 v62, v62, -v62, s[4:5]
	v_pk_fma_f32 v[50:51], v[50:51], v[84:85], v[62:63]
	v_mov_b32_e32 v62, v52
	v_mov_b32_e32 v63, v53
	s_nop 0
	v_permlane32_swap_b32_e32 v57, v62
	v_permlane32_swap_b32_e32 v63, v64
	v_cndmask_b32_e64 v63, v63, v64, s[4:5]
	v_cndmask_b32_e64 v62, v57, v62, s[4:5]
	v_mov_b32_e32 v65, v60
	v_mov_b32_e32 v60, v59
	v_mov_b32_e32 v64, v58
	v_pk_mul_f32 v[58:59], v[60:61], v[62:63]
	s_nop 0
	v_cndmask_b32_e64 v59, v59, -v59, s[4:5]
	v_cndmask_b32_e64 v58, v58, -v58, s[4:5]
	v_pk_fma_f32 v[52:53], v[52:53], v[64:65], v[58:59]

; template <int AI>
; __device__ __forceinline__ void epi_inproj(const Params& p, const acc8_t& acc, int g, int tbase, int fr, int fq) {
;     ...
;     if (rope) {
;       const int pos = sample ? 1024 + tl : trow + tl;
;       const float4* cs = (const float4*)((const float2*)(ws + OFF_CS) + (size_t)pos * 8 + 4 * (fq & 1));
;       const float4 c01 = cs[0], c23 = cs[1];
;       const float cc[4] = {c01.x, c01.z, c23.x, c23.z};
;       const float sn[4] = {c01.y, c01.w, c23.y, c23.w};
; #pragma unroll
;       for (int j = 0; j < 4; j++) {
;         const float other = xother32(x[j], fq < 2);
;         x[j] = (fq < 2) ? x[j] * cc[j] - other * sn[j] : x[j] * cc[j] + other * sn[j];
;       }
;     }
.LBB0_431:
	v_mov_b32_e32 v39, v34
	v_mov_b32_e32 v48, v34
	v_mov_b32_e32 v49, v35
	v_mov_b32_e32 v50, v35
	v_permlane32_swap_b32_e32 v39, v48
	s_nop 0
	v_permlane32_swap_b32_e32 v49, v50
	v_cndmask_b32_e64 v49, v49, v50, s[4:5]
	v_cndmask_b32_e64 v48, v39, v48, s[4:5]
	v_mov_b32_e32 v39, v36
	v_mov_b64_e32 v[40:41], v[222:223]
	v_mov_b64_e32 v[42:43], v[224:225]
	v_mov_b64_e32 v[44:45], v[226:227]
	v_mov_b64_e32 v[46:47], v[228:229]
	v_mov_b32_e32 v51, v46
	v_mov_b32_e32 v46, v45
	v_mov_b32_e32 v50, v44
	v_pk_mul_f32 v[44:45], v[46:47], v[48:49]
	v_mov_b32_e32 v46, v37
	v_cndmask_b32_e64 v45, v45, -v45, s[4:5]
	v_cndmask_b32_e64 v44, v44, -v44, s[4:5]
	v_pk_fma_f32 v[34:35], v[34:35], v[50:51], v[44:45]
	v_mov_b32_e32 v44, v36
	v_mov_b32_e32 v45, v37
	s_nop 0
	v_permlane32_swap_b32_e32 v39, v44
	v_permlane32_swap_b32_e32 v45, v46
	v_cndmask_b32_e64 v45, v45, v46, s[4:5]
	v_cndmask_b32_e64 v44, v39, v44, s[4:5]
	v_mov_b32_e32 v47, v42
	v_mov_b32_e32 v42, v41
	v_mov_b32_e32 v46, v40
	v_pk_mul_f32 v[40:41], v[42:43], v[44:45]
	s_nop 0
	v_cndmask_b32_e64 v41, v41, -v41, s[4:5]
	v_cndmask_b32_e64 v40, v40, -v40, s[4:5]
	v_pk_fma_f32 v[36:37], v[36:37], v[46:47], v[40:41]

; template <int AI>
; __device__ __forceinline__ void epi_inproj(const Params& p, const acc8_t& acc, int g, int tbase, int fr, int fq) {
;     ...
;     if (rope) {
;       const int pos = sample ? 1024 + tl : trow + tl;
;       const float4* cs = (const float4*)((const float2*)(ws + OFF_CS) + (size_t)pos * 8 + 4 * (fq & 1));
;       const float4 c01 = cs[0], c23 = cs[1];
;       const float cc[4] = {c01.x, c01.z, c23.x, c23.z};
;       const float sn[4] = {c01.y, c01.w, c23.y, c23.w};
; #pragma unroll
;       for (int j = 0; j < 4; j++) {
;         const float other = xother32(x[j], fq < 2);
;         x[j] = (fq < 2) ? x[j] * cc[j] - other * sn[j] : x[j] * cc[j] + other * sn[j];
;       }
;     }
.LBB0_445:
	v_mov_b32_e32 v23, v18
	v_mov_b32_e32 v32, v18
	v_mov_b32_e32 v33, v19
	v_mov_b32_e32 v34, v19
	v_permlane32_swap_b32_e32 v23, v32
	s_nop 0
	v_permlane32_swap_b32_e32 v33, v34
	v_cndmask_b32_e64 v33, v33, v34, s[4:5]
	v_cndmask_b32_e64 v32, v23, v32, s[4:5]
	v_mov_b32_e32 v23, v20
	v_mov_b64_e32 v[24:25], v[230:231]
	v_mov_b64_e32 v[26:27], v[232:233]
	v_mov_b64_e32 v[28:29], v[234:235]
	v_mov_b64_e32 v[30:31], v[236:237]
	v_mov_b32_e32 v35, v30
	v_mov_b32_e32 v30, v29
	v_mov_b32_e32 v34, v28
	v_pk_mul_f32 v[28:29], v[30:31], v[32:33]
	v_mov_b32_e32 v30, v21
	v_cndmask_b32_e64 v29, v29, -v29, s[4:5]
	v_cndmask_b32_e64 v28, v28, -v28, s[4:5]
	v_pk_fma_f32 v[18:19], v[18:19], v[34:35], v[28:29]
	v_mov_b32_e32 v28, v20
	v_mov_b32_e32 v29, v21
	s_nop 0
	v_permlane32_swap_b32_e32 v23, v28
	v_permlane32_swap_b32_e32 v29, v30
	v_cndmask_b32_e64 v29, v29, v30, s[4:5]
	v_cndmask_b32_e64 v28, v23, v28, s[4:5]
	v_mov_b32_e32 v31, v26
	v_mov_b32_e32 v26, v25
	v_mov_b32_e32 v30, v24
	v_pk_mul_f32 v[24:25], v[26:27], v[28:29]
	s_nop 0
	v_cndmask_b32_e64 v25, v25, -v25, s[4:5]
	v_cndmask_b32_e64 v24, v24, -v24, s[4:5]
	v_pk_fma_f32 v[20:21], v[20:21], v[30:31], v[24:25]
